# phase-3 gated short-conv loop hand-written: branch-free taps (clamped rows, zeroed gate), tap weights hoisted out of the item loop, next item's 7 loads in flight during the arithmetic (counted vmcnt)
# baseline (speedup 1.0000x reference)
.LBB0_272:
	s_or_b64 exec, exec, s[72:73]
	s_mov_b32 s0, 0xc0000
	v_cmp_gt_i32_e32 vcc, s0, v22
	s_and_saveexec_b64 s[0:1], vcc
	s_cbranch_execz .LBB0_281
	v_and_b32_e32 v60, 63, v22
	v_lshrrev_b32_e32 v61, 6, v22
	v_lshlrev_b32_e32 v62, 5, v60
	v_add_u32_e32 v63, 0x1000, v62
	v_lshlrev_b32_e32 v60, 4, v60
	global_load_dwordx4 v[64:67], v62, s[70:71]
	global_load_dwordx4 v[68:71], v62, s[70:71] offset:16
	global_load_dwordx4 v[72:75], v62, s[70:71] offset:2048
	global_load_dwordx4 v[76:79], v62, s[70:71] offset:2064
	global_load_dwordx4 v[80:83], v63, s[70:71]
	global_load_dwordx4 v[84:87], v63, s[70:71] offset:16
	v_lshlrev_b32_e32 v46, 12, v61
	v_add_u32_e32 v46, v46, v60
	v_mov_b32_e32 v47, 0
	v_lshl_add_u64 v[40:41], s[44:45], 0, v[46:47]
	v_lshlrev_b32_e32 v46, 11, v61
	v_add_u32_e32 v46, v46, v60
	v_add_u32_e32 v46, 0x400, v46
	v_lshl_add_u64 v[44:45], s[48:49], 0, v[46:47]
	s_mov_b64 s[4:5], 0x800000
	s_mov_b64 s[6:7], 0x400000
	v_mov_b32_e32 v49, 0xff
	v_mov_b32_e32 v48, 0x7ff
	v_cmp_gt_u32_e32 vcc, 0x1000, v61
	s_nop 1
	v_cndmask_b32_e32 v50, v48, v49, vcc
	v_and_b32_e32 v51, v50, v61
	v_cmp_ne_u32_e32 vcc, 0, v51
	s_nop 1
	v_cndmask_b32_e64 v128, 0, -1, vcc
	v_cmp_ne_u32_e32 vcc, v51, v50
	s_nop 1
	v_cndmask_b32_e64 v129, 0, -1, vcc
	v_and_b32_e32 v48, 0xfffff000, v128
	v_mov_b32_e32 v49, v128
	v_lshl_add_u64 v[46:47], v[40:41], 0, v[48:49]
	global_load_dwordx4 v[100:103], v[40:41], off offset:1024
	global_load_dwordx4 v[104:107], v[46:47], off offset:2048
	global_load_dwordx4 v[108:111], v[46:47], off offset:3072
	global_load_dwordx4 v[112:115], v[40:41], off offset:2048
	global_load_dwordx4 v[116:119], v[40:41], off offset:3072
	v_and_b32_e32 v48, 0x1000, v129
	v_mov_b32_e32 v49, 0
	v_lshl_add_u64 v[46:47], v[40:41], 0, v[48:49]
	global_load_dwordx4 v[120:123], v[46:47], off offset:2048
	global_load_dwordx4 v[124:127], v[46:47], off offset:3072
	v_add_u32_e32 v61, 0x800, v61
	v_lshl_add_u64 v[40:41], v[40:41], 0, s[4:5]
	v_mov_b32_e32 v49, 0xff
	v_mov_b32_e32 v48, 0x7ff
	v_cmp_gt_u32_e32 vcc, 0x1000, v61
	s_nop 1
	v_cndmask_b32_e32 v50, v48, v49, vcc
	v_and_b32_e32 v51, v50, v61
	v_cmp_ne_u32_e32 vcc, 0, v51
	s_nop 1
	v_cndmask_b32_e64 v160, 0, -1, vcc
	v_cmp_ne_u32_e32 vcc, v51, v50
	s_nop 1
	v_cndmask_b32_e64 v161, 0, -1, vcc
	v_and_b32_e32 v48, 0xfffff000, v160
	v_mov_b32_e32 v49, v160
	v_lshl_add_u64 v[46:47], v[40:41], 0, v[48:49]
	global_load_dwordx4 v[132:135], v[40:41], off offset:1024
	global_load_dwordx4 v[136:139], v[46:47], off offset:2048
	global_load_dwordx4 v[140:143], v[46:47], off offset:3072
	global_load_dwordx4 v[144:147], v[40:41], off offset:2048
	global_load_dwordx4 v[148:151], v[40:41], off offset:3072
	v_and_b32_e32 v48, 0x1000, v161
	v_mov_b32_e32 v49, 0
	v_lshl_add_u64 v[46:47], v[40:41], 0, v[48:49]
	global_load_dwordx4 v[152:155], v[46:47], off offset:2048
	global_load_dwordx4 v[156:159], v[46:47], off offset:3072
	s_waitcnt vmcnt(7)
	v_and_b32_e32 v104, v104, v128
	v_and_b32_e32 v120, v120, v129
	v_and_b32_e32 v105, v105, v128
	v_and_b32_e32 v121, v121, v129
	v_and_b32_e32 v106, v106, v128
	v_and_b32_e32 v122, v122, v129
	v_and_b32_e32 v107, v107, v128
	v_and_b32_e32 v123, v123, v129
	v_lshlrev_b32_e32 v96, 16, v104
	v_and_b32_e32 v97, 0xffff0000, v104
	v_lshlrev_b32_e32 v98, 16, v108
	v_and_b32_e32 v99, 0xffff0000, v108
	v_mul_f32_e32 v96, v64, v96
	v_mul_f32_e32 v97, v65, v97
	v_fma_f32 v88, v96, v98, 0
	v_fma_f32 v89, v97, v99, 0
	v_lshlrev_b32_e32 v96, 16, v105
	v_and_b32_e32 v97, 0xffff0000, v105
	v_lshlrev_b32_e32 v98, 16, v109
	v_and_b32_e32 v99, 0xffff0000, v109
	v_mul_f32_e32 v96, v66, v96
	v_mul_f32_e32 v97, v67, v97
	v_fma_f32 v90, v96, v98, 0
	v_fma_f32 v91, v97, v99, 0
	v_lshlrev_b32_e32 v96, 16, v106
	v_and_b32_e32 v97, 0xffff0000, v106
	v_lshlrev_b32_e32 v98, 16, v110
	v_and_b32_e32 v99, 0xffff0000, v110
	v_mul_f32_e32 v96, v68, v96
	v_mul_f32_e32 v97, v69, v97
	v_fma_f32 v92, v96, v98, 0
	v_fma_f32 v93, v97, v99, 0
	v_lshlrev_b32_e32 v96, 16, v107
	v_and_b32_e32 v97, 0xffff0000, v107
	v_lshlrev_b32_e32 v98, 16, v111
	v_and_b32_e32 v99, 0xffff0000, v111
	v_mul_f32_e32 v96, v70, v96
	v_mul_f32_e32 v97, v71, v97
	v_fma_f32 v94, v96, v98, 0
	v_fma_f32 v95, v97, v99, 0
	v_lshlrev_b32_e32 v96, 16, v112
	v_and_b32_e32 v97, 0xffff0000, v112
	v_lshlrev_b32_e32 v98, 16, v116
	v_and_b32_e32 v99, 0xffff0000, v116
	v_mul_f32_e32 v96, v72, v96
	v_mul_f32_e32 v97, v73, v97
	v_fmac_f32_e32 v88, v96, v98
	v_fmac_f32_e32 v89, v97, v99
	v_lshlrev_b32_e32 v96, 16, v113
	v_and_b32_e32 v97, 0xffff0000, v113
	v_lshlrev_b32_e32 v98, 16, v117
	v_and_b32_e32 v99, 0xffff0000, v117
	v_mul_f32_e32 v96, v74, v96
	v_mul_f32_e32 v97, v75, v97
	v_fmac_f32_e32 v90, v96, v98
	v_fmac_f32_e32 v91, v97, v99
	v_lshlrev_b32_e32 v96, 16, v114
	v_and_b32_e32 v97, 0xffff0000, v114
	v_lshlrev_b32_e32 v98, 16, v118
	v_and_b32_e32 v99, 0xffff0000, v118
	v_mul_f32_e32 v96, v76, v96
	v_mul_f32_e32 v97, v77, v97
	v_fmac_f32_e32 v92, v96, v98
	v_fmac_f32_e32 v93, v97, v99
	v_lshlrev_b32_e32 v96, 16, v115
	v_and_b32_e32 v97, 0xffff0000, v115
	v_lshlrev_b32_e32 v98, 16, v119
	v_and_b32_e32 v99, 0xffff0000, v119
	v_mul_f32_e32 v96, v78, v96
	v_mul_f32_e32 v97, v79, v97
	v_fmac_f32_e32 v94, v96, v98
	v_fmac_f32_e32 v95, v97, v99
	v_lshlrev_b32_e32 v96, 16, v120
	v_and_b32_e32 v97, 0xffff0000, v120
	v_lshlrev_b32_e32 v98, 16, v124
	v_and_b32_e32 v99, 0xffff0000, v124
	v_mul_f32_e32 v96, v80, v96
	v_mul_f32_e32 v97, v81, v97
	v_fmac_f32_e32 v88, v96, v98
	v_fmac_f32_e32 v89, v97, v99
	v_lshlrev_b32_e32 v96, 16, v121
	v_and_b32_e32 v97, 0xffff0000, v121
	v_lshlrev_b32_e32 v98, 16, v125
	v_and_b32_e32 v99, 0xffff0000, v125
	v_mul_f32_e32 v96, v82, v96
	v_mul_f32_e32 v97, v83, v97
	v_fmac_f32_e32 v90, v96, v98
	v_fmac_f32_e32 v91, v97, v99
	v_lshlrev_b32_e32 v96, 16, v122
	v_and_b32_e32 v97, 0xffff0000, v122
	v_lshlrev_b32_e32 v98, 16, v126
	v_and_b32_e32 v99, 0xffff0000, v126
	v_mul_f32_e32 v96, v84, v96
	v_mul_f32_e32 v97, v85, v97
	v_fmac_f32_e32 v92, v96, v98
	v_fmac_f32_e32 v93, v97, v99
	v_lshlrev_b32_e32 v96, 16, v123
	v_and_b32_e32 v97, 0xffff0000, v123
	v_lshlrev_b32_e32 v98, 16, v127
	v_and_b32_e32 v99, 0xffff0000, v127
	v_mul_f32_e32 v96, v86, v96
	v_mul_f32_e32 v97, v87, v97
	v_fmac_f32_e32 v94, v96, v98
	v_fmac_f32_e32 v95, v97, v99
	v_lshlrev_b32_e32 v96, 16, v100
	v_and_b32_e32 v97, 0xffff0000, v100
	v_mul_f32_e32 v88, v88, v96
	v_mul_f32_e32 v89, v89, v97
	v_lshlrev_b32_e32 v96, 16, v101
	v_and_b32_e32 v97, 0xffff0000, v101
	v_mul_f32_e32 v90, v90, v96
	v_mul_f32_e32 v91, v91, v97
	v_lshlrev_b32_e32 v96, 16, v102
	v_and_b32_e32 v97, 0xffff0000, v102
	v_mul_f32_e32 v92, v92, v96
	v_mul_f32_e32 v93, v93, v97
	v_lshlrev_b32_e32 v96, 16, v103
	v_and_b32_e32 v97, 0xffff0000, v103
	v_mul_f32_e32 v94, v94, v96
	v_mul_f32_e32 v95, v95, v97
	v_cvt_pk_bf16_f32 v52, v88, v89
	v_cvt_pk_bf16_f32 v53, v90, v91
	v_cvt_pk_bf16_f32 v54, v92, v93
	v_cvt_pk_bf16_f32 v55, v94, v95
	global_store_dwordx4 v[44:45], v[52:55], off
	v_lshl_add_u64 v[44:45], v[44:45], 0, s[6:7]
	v_add_u32_e32 v61, 0x800, v61
	v_lshl_add_u64 v[40:41], v[40:41], 0, s[4:5]
	v_mov_b32_e32 v49, 0xff
	v_mov_b32_e32 v48, 0x7ff
	v_cmp_gt_u32_e32 vcc, 0x1000, v61
	s_nop 1
	v_cndmask_b32_e32 v50, v48, v49, vcc
	v_and_b32_e32 v51, v50, v61
	v_cmp_ne_u32_e32 vcc, 0, v51
	s_nop 1
	v_cndmask_b32_e64 v128, 0, -1, vcc
	v_cmp_ne_u32_e32 vcc, v51, v50
	s_nop 1
	v_cndmask_b32_e64 v129, 0, -1, vcc
	v_and_b32_e32 v48, 0xfffff000, v128
	v_mov_b32_e32 v49, v128
	v_lshl_add_u64 v[46:47], v[40:41], 0, v[48:49]
	global_load_dwordx4 v[100:103], v[40:41], off offset:1024
	global_load_dwordx4 v[104:107], v[46:47], off offset:2048
	global_load_dwordx4 v[108:111], v[46:47], off offset:3072
	global_load_dwordx4 v[112:115], v[40:41], off offset:2048
	global_load_dwordx4 v[116:119], v[40:41], off offset:3072
	v_and_b32_e32 v48, 0x1000, v129
	v_mov_b32_e32 v49, 0
	v_lshl_add_u64 v[46:47], v[40:41], 0, v[48:49]
	global_load_dwordx4 v[120:123], v[46:47], off offset:2048
	global_load_dwordx4 v[124:127], v[46:47], off offset:3072
	s_waitcnt vmcnt(8)
	v_and_b32_e32 v136, v136, v160
	v_and_b32_e32 v152, v152, v161
	v_and_b32_e32 v137, v137, v160
	v_and_b32_e32 v153, v153, v161
	v_and_b32_e32 v138, v138, v160
	v_and_b32_e32 v154, v154, v161
	v_and_b32_e32 v139, v139, v160
	v_and_b32_e32 v155, v155, v161
	v_lshlrev_b32_e32 v96, 16, v136
	v_and_b32_e32 v97, 0xffff0000, v136
	v_lshlrev_b32_e32 v98, 16, v140
	v_and_b32_e32 v99, 0xffff0000, v140
	v_mul_f32_e32 v96, v64, v96
	v_mul_f32_e32 v97, v65, v97
	v_fma_f32 v88, v96, v98, 0
	v_fma_f32 v89, v97, v99, 0
	v_lshlrev_b32_e32 v96, 16, v137
	v_and_b32_e32 v97, 0xffff0000, v137
	v_lshlrev_b32_e32 v98, 16, v141
	v_and_b32_e32 v99, 0xffff0000, v141
	v_mul_f32_e32 v96, v66, v96
	v_mul_f32_e32 v97, v67, v97
	v_fma_f32 v90, v96, v98, 0
	v_fma_f32 v91, v97, v99, 0
	v_lshlrev_b32_e32 v96, 16, v138
	v_and_b32_e32 v97, 0xffff0000, v138
	v_lshlrev_b32_e32 v98, 16, v142
	v_and_b32_e32 v99, 0xffff0000, v142
	v_mul_f32_e32 v96, v68, v96
	v_mul_f32_e32 v97, v69, v97
	v_fma_f32 v92, v96, v98, 0
	v_fma_f32 v93, v97, v99, 0
	v_lshlrev_b32_e32 v96, 16, v139
	v_and_b32_e32 v97, 0xffff0000, v139
	v_lshlrev_b32_e32 v98, 16, v143
	v_and_b32_e32 v99, 0xffff0000, v143
	v_mul_f32_e32 v96, v70, v96
	v_mul_f32_e32 v97, v71, v97
	v_fma_f32 v94, v96, v98, 0
	v_fma_f32 v95, v97, v99, 0
	v_lshlrev_b32_e32 v96, 16, v144
	v_and_b32_e32 v97, 0xffff0000, v144
	v_lshlrev_b32_e32 v98, 16, v148
	v_and_b32_e32 v99, 0xffff0000, v148
	v_mul_f32_e32 v96, v72, v96
	v_mul_f32_e32 v97, v73, v97
	v_fmac_f32_e32 v88, v96, v98
	v_fmac_f32_e32 v89, v97, v99
	v_lshlrev_b32_e32 v96, 16, v145
	v_and_b32_e32 v97, 0xffff0000, v145
	v_lshlrev_b32_e32 v98, 16, v149
	v_and_b32_e32 v99, 0xffff0000, v149
	v_mul_f32_e32 v96, v74, v96
	v_mul_f32_e32 v97, v75, v97
	v_fmac_f32_e32 v90, v96, v98
	v_fmac_f32_e32 v91, v97, v99
	v_lshlrev_b32_e32 v96, 16, v146
	v_and_b32_e32 v97, 0xffff0000, v146
	v_lshlrev_b32_e32 v98, 16, v150
	v_and_b32_e32 v99, 0xffff0000, v150
	v_mul_f32_e32 v96, v76, v96
	v_mul_f32_e32 v97, v77, v97
	v_fmac_f32_e32 v92, v96, v98
	v_fmac_f32_e32 v93, v97, v99
	v_lshlrev_b32_e32 v96, 16, v147
	v_and_b32_e32 v97, 0xffff0000, v147
	v_lshlrev_b32_e32 v98, 16, v151
	v_and_b32_e32 v99, 0xffff0000, v151
	v_mul_f32_e32 v96, v78, v96
	v_mul_f32_e32 v97, v79, v97
	v_fmac_f32_e32 v94, v96, v98
	v_fmac_f32_e32 v95, v97, v99
	v_lshlrev_b32_e32 v96, 16, v152
	v_and_b32_e32 v97, 0xffff0000, v152
	v_lshlrev_b32_e32 v98, 16, v156
	v_and_b32_e32 v99, 0xffff0000, v156
	v_mul_f32_e32 v96, v80, v96
	v_mul_f32_e32 v97, v81, v97
	v_fmac_f32_e32 v88, v96, v98
	v_fmac_f32_e32 v89, v97, v99
	v_lshlrev_b32_e32 v96, 16, v153
	v_and_b32_e32 v97, 0xffff0000, v153
	v_lshlrev_b32_e32 v98, 16, v157
	v_and_b32_e32 v99, 0xffff0000, v157
	v_mul_f32_e32 v96, v82, v96
	v_mul_f32_e32 v97, v83, v97
	v_fmac_f32_e32 v90, v96, v98
	v_fmac_f32_e32 v91, v97, v99
	v_lshlrev_b32_e32 v96, 16, v154
	v_and_b32_e32 v97, 0xffff0000, v154
	v_lshlrev_b32_e32 v98, 16, v158
	v_and_b32_e32 v99, 0xffff0000, v158
	v_mul_f32_e32 v96, v84, v96
	v_mul_f32_e32 v97, v85, v97
	v_fmac_f32_e32 v92, v96, v98
	v_fmac_f32_e32 v93, v97, v99
	v_lshlrev_b32_e32 v96, 16, v155
	v_and_b32_e32 v97, 0xffff0000, v155
	v_lshlrev_b32_e32 v98, 16, v159
	v_and_b32_e32 v99, 0xffff0000, v159
	v_mul_f32_e32 v96, v86, v96
	v_mul_f32_e32 v97, v87, v97
	v_fmac_f32_e32 v94, v96, v98
	v_fmac_f32_e32 v95, v97, v99
	v_lshlrev_b32_e32 v96, 16, v132
	v_and_b32_e32 v97, 0xffff0000, v132
	v_mul_f32_e32 v88, v88, v96
	v_mul_f32_e32 v89, v89, v97
	v_lshlrev_b32_e32 v96, 16, v133
	v_and_b32_e32 v97, 0xffff0000, v133
	v_mul_f32_e32 v90, v90, v96
	v_mul_f32_e32 v91, v91, v97
	v_lshlrev_b32_e32 v96, 16, v134
	v_and_b32_e32 v97, 0xffff0000, v134
	v_mul_f32_e32 v92, v92, v96
	v_mul_f32_e32 v93, v93, v97
	v_lshlrev_b32_e32 v96, 16, v135
	v_and_b32_e32 v97, 0xffff0000, v135
	v_mul_f32_e32 v94, v94, v96
	v_mul_f32_e32 v95, v95, v97
	v_cvt_pk_bf16_f32 v52, v88, v89
	v_cvt_pk_bf16_f32 v53, v90, v91
	v_cvt_pk_bf16_f32 v54, v92, v93
	v_cvt_pk_bf16_f32 v55, v94, v95
	global_store_dwordx4 v[44:45], v[52:55], off
	v_lshl_add_u64 v[44:45], v[44:45], 0, s[6:7]
	v_add_u32_e32 v61, 0x800, v61
	v_lshl_add_u64 v[40:41], v[40:41], 0, s[4:5]
	v_mov_b32_e32 v49, 0xff
	v_mov_b32_e32 v48, 0x7ff
	v_cmp_gt_u32_e32 vcc, 0x1000, v61
	s_nop 1
	v_cndmask_b32_e32 v50, v48, v49, vcc
	v_and_b32_e32 v51, v50, v61
	v_cmp_ne_u32_e32 vcc, 0, v51
	s_nop 1
	v_cndmask_b32_e64 v160, 0, -1, vcc
	v_cmp_ne_u32_e32 vcc, v51, v50
	s_nop 1
	v_cndmask_b32_e64 v161, 0, -1, vcc
	v_and_b32_e32 v48, 0xfffff000, v160
	v_mov_b32_e32 v49, v160
	v_lshl_add_u64 v[46:47], v[40:41], 0, v[48:49]
	global_load_dwordx4 v[132:135], v[40:41], off offset:1024
	global_load_dwordx4 v[136:139], v[46:47], off offset:2048
	global_load_dwordx4 v[140:143], v[46:47], off offset:3072
	global_load_dwordx4 v[144:147], v[40:41], off offset:2048
	global_load_dwordx4 v[148:151], v[40:41], off offset:3072
	v_and_b32_e32 v48, 0x1000, v161
	v_mov_b32_e32 v49, 0
	v_lshl_add_u64 v[46:47], v[40:41], 0, v[48:49]
	global_load_dwordx4 v[152:155], v[46:47], off offset:2048
	global_load_dwordx4 v[156:159], v[46:47], off offset:3072
	s_waitcnt vmcnt(8)
	v_and_b32_e32 v104, v104, v128
	v_and_b32_e32 v120, v120, v129
	v_and_b32_e32 v105, v105, v128
	v_and_b32_e32 v121, v121, v129
	v_and_b32_e32 v106, v106, v128
	v_and_b32_e32 v122, v122, v129
	v_and_b32_e32 v107, v107, v128
	v_and_b32_e32 v123, v123, v129
	v_lshlrev_b32_e32 v96, 16, v104
	v_and_b32_e32 v97, 0xffff0000, v104
	v_lshlrev_b32_e32 v98, 16, v108
	v_and_b32_e32 v99, 0xffff0000, v108
	v_mul_f32_e32 v96, v64, v96
	v_mul_f32_e32 v97, v65, v97
	v_fma_f32 v88, v96, v98, 0
	v_fma_f32 v89, v97, v99, 0
	v_lshlrev_b32_e32 v96, 16, v105
	v_and_b32_e32 v97, 0xffff0000, v105
	v_lshlrev_b32_e32 v98, 16, v109
	v_and_b32_e32 v99, 0xffff0000, v109
	v_mul_f32_e32 v96, v66, v96
	v_mul_f32_e32 v97, v67, v97
	v_fma_f32 v90, v96, v98, 0
	v_fma_f32 v91, v97, v99, 0
	v_lshlrev_b32_e32 v96, 16, v106
	v_and_b32_e32 v97, 0xffff0000, v106
	v_lshlrev_b32_e32 v98, 16, v110
	v_and_b32_e32 v99, 0xffff0000, v110
	v_mul_f32_e32 v96, v68, v96
	v_mul_f32_e32 v97, v69, v97
	v_fma_f32 v92, v96, v98, 0
	v_fma_f32 v93, v97, v99, 0
	v_lshlrev_b32_e32 v96, 16, v107
	v_and_b32_e32 v97, 0xffff0000, v107
	v_lshlrev_b32_e32 v98, 16, v111
	v_and_b32_e32 v99, 0xffff0000, v111
	v_mul_f32_e32 v96, v70, v96
	v_mul_f32_e32 v97, v71, v97
	v_fma_f32 v94, v96, v98, 0
	v_fma_f32 v95, v97, v99, 0
	v_lshlrev_b32_e32 v96, 16, v112
	v_and_b32_e32 v97, 0xffff0000, v112
	v_lshlrev_b32_e32 v98, 16, v116
	v_and_b32_e32 v99, 0xffff0000, v116
	v_mul_f32_e32 v96, v72, v96
	v_mul_f32_e32 v97, v73, v97
	v_fmac_f32_e32 v88, v96, v98
	v_fmac_f32_e32 v89, v97, v99
	v_lshlrev_b32_e32 v96, 16, v113
	v_and_b32_e32 v97, 0xffff0000, v113
	v_lshlrev_b32_e32 v98, 16, v117
	v_and_b32_e32 v99, 0xffff0000, v117
	v_mul_f32_e32 v96, v74, v96
	v_mul_f32_e32 v97, v75, v97
	v_fmac_f32_e32 v90, v96, v98
	v_fmac_f32_e32 v91, v97, v99
	v_lshlrev_b32_e32 v96, 16, v114
	v_and_b32_e32 v97, 0xffff0000, v114
	v_lshlrev_b32_e32 v98, 16, v118
	v_and_b32_e32 v99, 0xffff0000, v118
	v_mul_f32_e32 v96, v76, v96
	v_mul_f32_e32 v97, v77, v97
	v_fmac_f32_e32 v92, v96, v98
	v_fmac_f32_e32 v93, v97, v99
	v_lshlrev_b32_e32 v96, 16, v115
	v_and_b32_e32 v97, 0xffff0000, v115
	v_lshlrev_b32_e32 v98, 16, v119
	v_and_b32_e32 v99, 0xffff0000, v119
	v_mul_f32_e32 v96, v78, v96
	v_mul_f32_e32 v97, v79, v97
	v_fmac_f32_e32 v94, v96, v98
	v_fmac_f32_e32 v95, v97, v99
	v_lshlrev_b32_e32 v96, 16, v120
	v_and_b32_e32 v97, 0xffff0000, v120
	v_lshlrev_b32_e32 v98, 16, v124
	v_and_b32_e32 v99, 0xffff0000, v124
	v_mul_f32_e32 v96, v80, v96
	v_mul_f32_e32 v97, v81, v97
	v_fmac_f32_e32 v88, v96, v98
	v_fmac_f32_e32 v89, v97, v99
	v_lshlrev_b32_e32 v96, 16, v121
	v_and_b32_e32 v97, 0xffff0000, v121
	v_lshlrev_b32_e32 v98, 16, v125
	v_and_b32_e32 v99, 0xffff0000, v125
	v_mul_f32_e32 v96, v82, v96
	v_mul_f32_e32 v97, v83, v97
	v_fmac_f32_e32 v90, v96, v98
	v_fmac_f32_e32 v91, v97, v99
	v_lshlrev_b32_e32 v96, 16, v122
	v_and_b32_e32 v97, 0xffff0000, v122
	v_lshlrev_b32_e32 v98, 16, v126
	v_and_b32_e32 v99, 0xffff0000, v126
	v_mul_f32_e32 v96, v84, v96
	v_mul_f32_e32 v97, v85, v97
	v_fmac_f32_e32 v92, v96, v98
	v_fmac_f32_e32 v93, v97, v99
	v_lshlrev_b32_e32 v96, 16, v123
	v_and_b32_e32 v97, 0xffff0000, v123
	v_lshlrev_b32_e32 v98, 16, v127
	v_and_b32_e32 v99, 0xffff0000, v127
	v_mul_f32_e32 v96, v86, v96
	v_mul_f32_e32 v97, v87, v97
	v_fmac_f32_e32 v94, v96, v98
	v_fmac_f32_e32 v95, v97, v99
	v_lshlrev_b32_e32 v96, 16, v100
	v_and_b32_e32 v97, 0xffff0000, v100
	v_mul_f32_e32 v88, v88, v96
	v_mul_f32_e32 v89, v89, v97
	v_lshlrev_b32_e32 v96, 16, v101
	v_and_b32_e32 v97, 0xffff0000, v101
	v_mul_f32_e32 v90, v90, v96
	v_mul_f32_e32 v91, v91, v97
	v_lshlrev_b32_e32 v96, 16, v102
	v_and_b32_e32 v97, 0xffff0000, v102
	v_mul_f32_e32 v92, v92, v96
	v_mul_f32_e32 v93, v93, v97
	v_lshlrev_b32_e32 v96, 16, v103
	v_and_b32_e32 v97, 0xffff0000, v103
	v_mul_f32_e32 v94, v94, v96
	v_mul_f32_e32 v95, v95, v97
	v_cvt_pk_bf16_f32 v52, v88, v89
	v_cvt_pk_bf16_f32 v53, v90, v91
	v_cvt_pk_bf16_f32 v54, v92, v93
	v_cvt_pk_bf16_f32 v55, v94, v95
	global_store_dwordx4 v[44:45], v[52:55], off
	v_lshl_add_u64 v[44:45], v[44:45], 0, s[6:7]
	v_add_u32_e32 v61, 0x800, v61
	v_lshl_add_u64 v[40:41], v[40:41], 0, s[4:5]
	v_mov_b32_e32 v49, 0xff
	v_mov_b32_e32 v48, 0x7ff
	v_cmp_gt_u32_e32 vcc, 0x1000, v61
	s_nop 1
	v_cndmask_b32_e32 v50, v48, v49, vcc
	v_and_b32_e32 v51, v50, v61
	v_cmp_ne_u32_e32 vcc, 0, v51
	s_nop 1
	v_cndmask_b32_e64 v128, 0, -1, vcc
	v_cmp_ne_u32_e32 vcc, v51, v50
	s_nop 1
	v_cndmask_b32_e64 v129, 0, -1, vcc
	v_and_b32_e32 v48, 0xfffff000, v128
	v_mov_b32_e32 v49, v128
	v_lshl_add_u64 v[46:47], v[40:41], 0, v[48:49]
	global_load_dwordx4 v[100:103], v[40:41], off offset:1024
	global_load_dwordx4 v[104:107], v[46:47], off offset:2048
	global_load_dwordx4 v[108:111], v[46:47], off offset:3072
	global_load_dwordx4 v[112:115], v[40:41], off offset:2048
	global_load_dwordx4 v[116:119], v[40:41], off offset:3072
	v_and_b32_e32 v48, 0x1000, v129
	v_mov_b32_e32 v49, 0
	v_lshl_add_u64 v[46:47], v[40:41], 0, v[48:49]
	global_load_dwordx4 v[120:123], v[46:47], off offset:2048
	global_load_dwordx4 v[124:127], v[46:47], off offset:3072
	s_waitcnt vmcnt(8)
	v_and_b32_e32 v136, v136, v160
	v_and_b32_e32 v152, v152, v161
	v_and_b32_e32 v137, v137, v160
	v_and_b32_e32 v153, v153, v161
	v_and_b32_e32 v138, v138, v160
	v_and_b32_e32 v154, v154, v161
	v_and_b32_e32 v139, v139, v160
	v_and_b32_e32 v155, v155, v161
	v_lshlrev_b32_e32 v96, 16, v136
	v_and_b32_e32 v97, 0xffff0000, v136
	v_lshlrev_b32_e32 v98, 16, v140
	v_and_b32_e32 v99, 0xffff0000, v140
	v_mul_f32_e32 v96, v64, v96
	v_mul_f32_e32 v97, v65, v97
	v_fma_f32 v88, v96, v98, 0
	v_fma_f32 v89, v97, v99, 0
	v_lshlrev_b32_e32 v96, 16, v137
	v_and_b32_e32 v97, 0xffff0000, v137
	v_lshlrev_b32_e32 v98, 16, v141
	v_and_b32_e32 v99, 0xffff0000, v141
	v_mul_f32_e32 v96, v66, v96
	v_mul_f32_e32 v97, v67, v97
	v_fma_f32 v90, v96, v98, 0
	v_fma_f32 v91, v97, v99, 0
	v_lshlrev_b32_e32 v96, 16, v138
	v_and_b32_e32 v97, 0xffff0000, v138
	v_lshlrev_b32_e32 v98, 16, v142
	v_and_b32_e32 v99, 0xffff0000, v142
	v_mul_f32_e32 v96, v68, v96
	v_mul_f32_e32 v97, v69, v97
	v_fma_f32 v92, v96, v98, 0
	v_fma_f32 v93, v97, v99, 0
	v_lshlrev_b32_e32 v96, 16, v139
	v_and_b32_e32 v97, 0xffff0000, v139
	v_lshlrev_b32_e32 v98, 16, v143
	v_and_b32_e32 v99, 0xffff0000, v143
	v_mul_f32_e32 v96, v70, v96
	v_mul_f32_e32 v97, v71, v97
	v_fma_f32 v94, v96, v98, 0
	v_fma_f32 v95, v97, v99, 0
	v_lshlrev_b32_e32 v96, 16, v144
	v_and_b32_e32 v97, 0xffff0000, v144
	v_lshlrev_b32_e32 v98, 16, v148
	v_and_b32_e32 v99, 0xffff0000, v148
	v_mul_f32_e32 v96, v72, v96
	v_mul_f32_e32 v97, v73, v97
	v_fmac_f32_e32 v88, v96, v98
	v_fmac_f32_e32 v89, v97, v99
	v_lshlrev_b32_e32 v96, 16, v145
	v_and_b32_e32 v97, 0xffff0000, v145
	v_lshlrev_b32_e32 v98, 16, v149
	v_and_b32_e32 v99, 0xffff0000, v149
	v_mul_f32_e32 v96, v74, v96
	v_mul_f32_e32 v97, v75, v97
	v_fmac_f32_e32 v90, v96, v98
	v_fmac_f32_e32 v91, v97, v99
	v_lshlrev_b32_e32 v96, 16, v146
	v_and_b32_e32 v97, 0xffff0000, v146
	v_lshlrev_b32_e32 v98, 16, v150
	v_and_b32_e32 v99, 0xffff0000, v150
	v_mul_f32_e32 v96, v76, v96
	v_mul_f32_e32 v97, v77, v97
	v_fmac_f32_e32 v92, v96, v98
	v_fmac_f32_e32 v93, v97, v99
	v_lshlrev_b32_e32 v96, 16, v147
	v_and_b32_e32 v97, 0xffff0000, v147
	v_lshlrev_b32_e32 v98, 16, v151
	v_and_b32_e32 v99, 0xffff0000, v151
	v_mul_f32_e32 v96, v78, v96
	v_mul_f32_e32 v97, v79, v97
	v_fmac_f32_e32 v94, v96, v98
	v_fmac_f32_e32 v95, v97, v99
	v_lshlrev_b32_e32 v96, 16, v152
	v_and_b32_e32 v97, 0xffff0000, v152
	v_lshlrev_b32_e32 v98, 16, v156
	v_and_b32_e32 v99, 0xffff0000, v156
	v_mul_f32_e32 v96, v80, v96
	v_mul_f32_e32 v97, v81, v97
	v_fmac_f32_e32 v88, v96, v98
	v_fmac_f32_e32 v89, v97, v99
	v_lshlrev_b32_e32 v96, 16, v153
	v_and_b32_e32 v97, 0xffff0000, v153
	v_lshlrev_b32_e32 v98, 16, v157
	v_and_b32_e32 v99, 0xffff0000, v157
	v_mul_f32_e32 v96, v82, v96
	v_mul_f32_e32 v97, v83, v97
	v_fmac_f32_e32 v90, v96, v98
	v_fmac_f32_e32 v91, v97, v99
	v_lshlrev_b32_e32 v96, 16, v154
	v_and_b32_e32 v97, 0xffff0000, v154
	v_lshlrev_b32_e32 v98, 16, v158
	v_and_b32_e32 v99, 0xffff0000, v158
	v_mul_f32_e32 v96, v84, v96
	v_mul_f32_e32 v97, v85, v97
	v_fmac_f32_e32 v92, v96, v98
	v_fmac_f32_e32 v93, v97, v99
	v_lshlrev_b32_e32 v96, 16, v155
	v_and_b32_e32 v97, 0xffff0000, v155
	v_lshlrev_b32_e32 v98, 16, v159
	v_and_b32_e32 v99, 0xffff0000, v159
	v_mul_f32_e32 v96, v86, v96
	v_mul_f32_e32 v97, v87, v97
	v_fmac_f32_e32 v94, v96, v98
	v_fmac_f32_e32 v95, v97, v99
	v_lshlrev_b32_e32 v96, 16, v132
	v_and_b32_e32 v97, 0xffff0000, v132
	v_mul_f32_e32 v88, v88, v96
	v_mul_f32_e32 v89, v89, v97
	v_lshlrev_b32_e32 v96, 16, v133
	v_and_b32_e32 v97, 0xffff0000, v133
	v_mul_f32_e32 v90, v90, v96
	v_mul_f32_e32 v91, v91, v97
	v_lshlrev_b32_e32 v96, 16, v134
	v_and_b32_e32 v97, 0xffff0000, v134
	v_mul_f32_e32 v92, v92, v96
	v_mul_f32_e32 v93, v93, v97
	v_lshlrev_b32_e32 v96, 16, v135
	v_and_b32_e32 v97, 0xffff0000, v135
	v_mul_f32_e32 v94, v94, v96
	v_mul_f32_e32 v95, v95, v97
	v_cvt_pk_bf16_f32 v52, v88, v89
	v_cvt_pk_bf16_f32 v53, v90, v91
	v_cvt_pk_bf16_f32 v54, v92, v93
	v_cvt_pk_bf16_f32 v55, v94, v95
	global_store_dwordx4 v[44:45], v[52:55], off
	v_lshl_add_u64 v[44:45], v[44:45], 0, s[6:7]
	v_add_u32_e32 v61, 0x800, v61
	v_lshl_add_u64 v[40:41], v[40:41], 0, s[4:5]
	v_mov_b32_e32 v49, 0xff
	v_mov_b32_e32 v48, 0x7ff
	v_cmp_gt_u32_e32 vcc, 0x1000, v61
	s_nop 1
	v_cndmask_b32_e32 v50, v48, v49, vcc
	v_and_b32_e32 v51, v50, v61
	v_cmp_ne_u32_e32 vcc, 0, v51
	s_nop 1
	v_cndmask_b32_e64 v160, 0, -1, vcc
	v_cmp_ne_u32_e32 vcc, v51, v50
	s_nop 1
	v_cndmask_b32_e64 v161, 0, -1, vcc
	v_and_b32_e32 v48, 0xfffff000, v160
	v_mov_b32_e32 v49, v160
	v_lshl_add_u64 v[46:47], v[40:41], 0, v[48:49]
	global_load_dwordx4 v[132:135], v[40:41], off offset:1024
	global_load_dwordx4 v[136:139], v[46:47], off offset:2048
	global_load_dwordx4 v[140:143], v[46:47], off offset:3072
	global_load_dwordx4 v[144:147], v[40:41], off offset:2048
	global_load_dwordx4 v[148:151], v[40:41], off offset:3072
	v_and_b32_e32 v48, 0x1000, v161
	v_mov_b32_e32 v49, 0
	v_lshl_add_u64 v[46:47], v[40:41], 0, v[48:49]
	global_load_dwordx4 v[152:155], v[46:47], off offset:2048
	global_load_dwordx4 v[156:159], v[46:47], off offset:3072
	s_waitcnt vmcnt(8)
	v_and_b32_e32 v104, v104, v128
	v_and_b32_e32 v120, v120, v129
	v_and_b32_e32 v105, v105, v128
	v_and_b32_e32 v121, v121, v129
	v_and_b32_e32 v106, v106, v128
	v_and_b32_e32 v122, v122, v129
	v_and_b32_e32 v107, v107, v128
	v_and_b32_e32 v123, v123, v129
	v_lshlrev_b32_e32 v96, 16, v104
	v_and_b32_e32 v97, 0xffff0000, v104
	v_lshlrev_b32_e32 v98, 16, v108
	v_and_b32_e32 v99, 0xffff0000, v108
	v_mul_f32_e32 v96, v64, v96
	v_mul_f32_e32 v97, v65, v97
	v_fma_f32 v88, v96, v98, 0
	v_fma_f32 v89, v97, v99, 0
	v_lshlrev_b32_e32 v96, 16, v105
	v_and_b32_e32 v97, 0xffff0000, v105
	v_lshlrev_b32_e32 v98, 16, v109
	v_and_b32_e32 v99, 0xffff0000, v109
	v_mul_f32_e32 v96, v66, v96
	v_mul_f32_e32 v97, v67, v97
	v_fma_f32 v90, v96, v98, 0
	v_fma_f32 v91, v97, v99, 0
	v_lshlrev_b32_e32 v96, 16, v106
	v_and_b32_e32 v97, 0xffff0000, v106
	v_lshlrev_b32_e32 v98, 16, v110
	v_and_b32_e32 v99, 0xffff0000, v110
	v_mul_f32_e32 v96, v68, v96
	v_mul_f32_e32 v97, v69, v97
	v_fma_f32 v92, v96, v98, 0
	v_fma_f32 v93, v97, v99, 0
	v_lshlrev_b32_e32 v96, 16, v107
	v_and_b32_e32 v97, 0xffff0000, v107
	v_lshlrev_b32_e32 v98, 16, v111
	v_and_b32_e32 v99, 0xffff0000, v111
	v_mul_f32_e32 v96, v70, v96
	v_mul_f32_e32 v97, v71, v97
	v_fma_f32 v94, v96, v98, 0
	v_fma_f32 v95, v97, v99, 0
	v_lshlrev_b32_e32 v96, 16, v112
	v_and_b32_e32 v97, 0xffff0000, v112
	v_lshlrev_b32_e32 v98, 16, v116
	v_and_b32_e32 v99, 0xffff0000, v116
	v_mul_f32_e32 v96, v72, v96
	v_mul_f32_e32 v97, v73, v97
	v_fmac_f32_e32 v88, v96, v98
	v_fmac_f32_e32 v89, v97, v99
	v_lshlrev_b32_e32 v96, 16, v113
	v_and_b32_e32 v97, 0xffff0000, v113
	v_lshlrev_b32_e32 v98, 16, v117
	v_and_b32_e32 v99, 0xffff0000, v117
	v_mul_f32_e32 v96, v74, v96
	v_mul_f32_e32 v97, v75, v97
	v_fmac_f32_e32 v90, v96, v98
	v_fmac_f32_e32 v91, v97, v99
	v_lshlrev_b32_e32 v96, 16, v114
	v_and_b32_e32 v97, 0xffff0000, v114
	v_lshlrev_b32_e32 v98, 16, v118
	v_and_b32_e32 v99, 0xffff0000, v118
	v_mul_f32_e32 v96, v76, v96
	v_mul_f32_e32 v97, v77, v97
	v_fmac_f32_e32 v92, v96, v98
	v_fmac_f32_e32 v93, v97, v99
	v_lshlrev_b32_e32 v96, 16, v115
	v_and_b32_e32 v97, 0xffff0000, v115
	v_lshlrev_b32_e32 v98, 16, v119
	v_and_b32_e32 v99, 0xffff0000, v119
	v_mul_f32_e32 v96, v78, v96
	v_mul_f32_e32 v97, v79, v97
	v_fmac_f32_e32 v94, v96, v98
	v_fmac_f32_e32 v95, v97, v99
	v_lshlrev_b32_e32 v96, 16, v120
	v_and_b32_e32 v97, 0xffff0000, v120
	v_lshlrev_b32_e32 v98, 16, v124
	v_and_b32_e32 v99, 0xffff0000, v124
	v_mul_f32_e32 v96, v80, v96
	v_mul_f32_e32 v97, v81, v97
	v_fmac_f32_e32 v88, v96, v98
	v_fmac_f32_e32 v89, v97, v99
	v_lshlrev_b32_e32 v96, 16, v121
	v_and_b32_e32 v97, 0xffff0000, v121
	v_lshlrev_b32_e32 v98, 16, v125
	v_and_b32_e32 v99, 0xffff0000, v125
	v_mul_f32_e32 v96, v82, v96
	v_mul_f32_e32 v97, v83, v97
	v_fmac_f32_e32 v90, v96, v98
	v_fmac_f32_e32 v91, v97, v99
	v_lshlrev_b32_e32 v96, 16, v122
	v_and_b32_e32 v97, 0xffff0000, v122
	v_lshlrev_b32_e32 v98, 16, v126
	v_and_b32_e32 v99, 0xffff0000, v126
	v_mul_f32_e32 v96, v84, v96
	v_mul_f32_e32 v97, v85, v97
	v_fmac_f32_e32 v92, v96, v98
	v_fmac_f32_e32 v93, v97, v99
	v_lshlrev_b32_e32 v96, 16, v123
	v_and_b32_e32 v97, 0xffff0000, v123
	v_lshlrev_b32_e32 v98, 16, v127
	v_and_b32_e32 v99, 0xffff0000, v127
	v_mul_f32_e32 v96, v86, v96
	v_mul_f32_e32 v97, v87, v97
	v_fmac_f32_e32 v94, v96, v98
	v_fmac_f32_e32 v95, v97, v99
	v_lshlrev_b32_e32 v96, 16, v100
	v_and_b32_e32 v97, 0xffff0000, v100
	v_mul_f32_e32 v88, v88, v96
	v_mul_f32_e32 v89, v89, v97
	v_lshlrev_b32_e32 v96, 16, v101
	v_and_b32_e32 v97, 0xffff0000, v101
	v_mul_f32_e32 v90, v90, v96
	v_mul_f32_e32 v91, v91, v97
	v_lshlrev_b32_e32 v96, 16, v102
	v_and_b32_e32 v97, 0xffff0000, v102
	v_mul_f32_e32 v92, v92, v96
	v_mul_f32_e32 v93, v93, v97
	v_lshlrev_b32_e32 v96, 16, v103
	v_and_b32_e32 v97, 0xffff0000, v103
	v_mul_f32_e32 v94, v94, v96
	v_mul_f32_e32 v95, v95, v97
	v_cvt_pk_bf16_f32 v52, v88, v89
	v_cvt_pk_bf16_f32 v53, v90, v91
	v_cvt_pk_bf16_f32 v54, v92, v93
	v_cvt_pk_bf16_f32 v55, v94, v95
	global_store_dwordx4 v[44:45], v[52:55], off
	v_lshl_add_u64 v[44:45], v[44:45], 0, s[6:7]
	s_waitcnt vmcnt(1)
	v_and_b32_e32 v136, v136, v160
	v_and_b32_e32 v152, v152, v161
	v_and_b32_e32 v137, v137, v160
	v_and_b32_e32 v153, v153, v161
	v_and_b32_e32 v138, v138, v160
	v_and_b32_e32 v154, v154, v161
	v_and_b32_e32 v139, v139, v160
	v_and_b32_e32 v155, v155, v161
	v_lshlrev_b32_e32 v96, 16, v136
	v_and_b32_e32 v97, 0xffff0000, v136
	v_lshlrev_b32_e32 v98, 16, v140
	v_and_b32_e32 v99, 0xffff0000, v140
	v_mul_f32_e32 v96, v64, v96
	v_mul_f32_e32 v97, v65, v97
	v_fma_f32 v88, v96, v98, 0
	v_fma_f32 v89, v97, v99, 0
	v_lshlrev_b32_e32 v96, 16, v137
	v_and_b32_e32 v97, 0xffff0000, v137
	v_lshlrev_b32_e32 v98, 16, v141
	v_and_b32_e32 v99, 0xffff0000, v141
	v_mul_f32_e32 v96, v66, v96
	v_mul_f32_e32 v97, v67, v97
	v_fma_f32 v90, v96, v98, 0
	v_fma_f32 v91, v97, v99, 0
	v_lshlrev_b32_e32 v96, 16, v138
	v_and_b32_e32 v97, 0xffff0000, v138
	v_lshlrev_b32_e32 v98, 16, v142
	v_and_b32_e32 v99, 0xffff0000, v142
	v_mul_f32_e32 v96, v68, v96
	v_mul_f32_e32 v97, v69, v97
	v_fma_f32 v92, v96, v98, 0
	v_fma_f32 v93, v97, v99, 0
	v_lshlrev_b32_e32 v96, 16, v139
	v_and_b32_e32 v97, 0xffff0000, v139
	v_lshlrev_b32_e32 v98, 16, v143
	v_and_b32_e32 v99, 0xffff0000, v143
	v_mul_f32_e32 v96, v70, v96
	v_mul_f32_e32 v97, v71, v97
	v_fma_f32 v94, v96, v98, 0
	v_fma_f32 v95, v97, v99, 0
	v_lshlrev_b32_e32 v96, 16, v144
	v_and_b32_e32 v97, 0xffff0000, v144
	v_lshlrev_b32_e32 v98, 16, v148
	v_and_b32_e32 v99, 0xffff0000, v148
	v_mul_f32_e32 v96, v72, v96
	v_mul_f32_e32 v97, v73, v97
	v_fmac_f32_e32 v88, v96, v98
	v_fmac_f32_e32 v89, v97, v99
	v_lshlrev_b32_e32 v96, 16, v145
	v_and_b32_e32 v97, 0xffff0000, v145
	v_lshlrev_b32_e32 v98, 16, v149
	v_and_b32_e32 v99, 0xffff0000, v149
	v_mul_f32_e32 v96, v74, v96
	v_mul_f32_e32 v97, v75, v97
	v_fmac_f32_e32 v90, v96, v98
	v_fmac_f32_e32 v91, v97, v99
	v_lshlrev_b32_e32 v96, 16, v146
	v_and_b32_e32 v97, 0xffff0000, v146
	v_lshlrev_b32_e32 v98, 16, v150
	v_and_b32_e32 v99, 0xffff0000, v150
	v_mul_f32_e32 v96, v76, v96
	v_mul_f32_e32 v97, v77, v97
	v_fmac_f32_e32 v92, v96, v98
	v_fmac_f32_e32 v93, v97, v99
	v_lshlrev_b32_e32 v96, 16, v147
	v_and_b32_e32 v97, 0xffff0000, v147
	v_lshlrev_b32_e32 v98, 16, v151
	v_and_b32_e32 v99, 0xffff0000, v151
	v_mul_f32_e32 v96, v78, v96
	v_mul_f32_e32 v97, v79, v97
	v_fmac_f32_e32 v94, v96, v98
	v_fmac_f32_e32 v95, v97, v99
	v_lshlrev_b32_e32 v96, 16, v152
	v_and_b32_e32 v97, 0xffff0000, v152
	v_lshlrev_b32_e32 v98, 16, v156
	v_and_b32_e32 v99, 0xffff0000, v156
	v_mul_f32_e32 v96, v80, v96
	v_mul_f32_e32 v97, v81, v97
	v_fmac_f32_e32 v88, v96, v98
	v_fmac_f32_e32 v89, v97, v99
	v_lshlrev_b32_e32 v96, 16, v153
	v_and_b32_e32 v97, 0xffff0000, v153
	v_lshlrev_b32_e32 v98, 16, v157
	v_and_b32_e32 v99, 0xffff0000, v157
	v_mul_f32_e32 v96, v82, v96
	v_mul_f32_e32 v97, v83, v97
	v_fmac_f32_e32 v90, v96, v98
	v_fmac_f32_e32 v91, v97, v99
	v_lshlrev_b32_e32 v96, 16, v154
	v_and_b32_e32 v97, 0xffff0000, v154
	v_lshlrev_b32_e32 v98, 16, v158
	v_and_b32_e32 v99, 0xffff0000, v158
	v_mul_f32_e32 v96, v84, v96
	v_mul_f32_e32 v97, v85, v97
	v_fmac_f32_e32 v92, v96, v98
	v_fmac_f32_e32 v93, v97, v99
	v_lshlrev_b32_e32 v96, 16, v155
	v_and_b32_e32 v97, 0xffff0000, v155
	v_lshlrev_b32_e32 v98, 16, v159
	v_and_b32_e32 v99, 0xffff0000, v159
	v_mul_f32_e32 v96, v86, v96
	v_mul_f32_e32 v97, v87, v97
	v_fmac_f32_e32 v94, v96, v98
	v_fmac_f32_e32 v95, v97, v99
	v_lshlrev_b32_e32 v96, 16, v132
	v_and_b32_e32 v97, 0xffff0000, v132
	v_mul_f32_e32 v88, v88, v96
	v_mul_f32_e32 v89, v89, v97
	v_lshlrev_b32_e32 v96, 16, v133
	v_and_b32_e32 v97, 0xffff0000, v133
	v_mul_f32_e32 v90, v90, v96
	v_mul_f32_e32 v91, v91, v97
	v_lshlrev_b32_e32 v96, 16, v134
	v_and_b32_e32 v97, 0xffff0000, v134
	v_mul_f32_e32 v92, v92, v96
	v_mul_f32_e32 v93, v93, v97
	v_lshlrev_b32_e32 v96, 16, v135
	v_and_b32_e32 v97, 0xffff0000, v135
	v_mul_f32_e32 v94, v94, v96
	v_mul_f32_e32 v95, v95, v97
	v_cvt_pk_bf16_f32 v52, v88, v89
	v_cvt_pk_bf16_f32 v53, v90, v91
	v_cvt_pk_bf16_f32 v54, v92, v93
	v_cvt_pk_bf16_f32 v55, v94, v95
	global_store_dwordx4 v[44:45], v[52:55], off
	v_lshl_add_u64 v[44:45], v[44:45], 0, s[6:7]
